# stack3 + in-projection GEMM: first K iteration of a tile waits vmcnt(24) so the previous tile's 16 epilogue stores stay in flight; prologue retires its own DMAs
# baseline (speedup 1.0000x reference)
; #define PG8_STAGE(bufoff, gbase, voff) do { _Pragma("unroll") for (int _i = 0; _i < 2; ++_i) \
;         __builtin_amdgcn_global_load_lds((const unsigned*)((const char*)(gbase) + (voff)[_i]), (PG8_LAS unsigned*)(lds + (bufoff) + ldsw + _i * 8192), 16, 0, 0); } while (0)
; #define PG8_LDA(dst, b, h) do { _Pragma("unroll") for (int m = 0; m < 4; ++m) _Pragma("unroll") for (int k = 0; k < 2; ++k) dst[m][k] = *(const PG8_LAS bf16x8*)(lds + PG8_SA(b, h) + aoff + m * 2048 + k * 1024); } while (0)
; #define PG8_LDB(dst, b, h) do { _Pragma("unroll") for (int n = 0; n < 2; ++n) _Pragma("unroll") for (int k = 0; k < 2; ++k) dst[n][k] = *(const PG8_LAS bf16x8*)(lds + PG8_SB(b, h) + boff + n * 2048 + k * 1024); } while (0)
; #define PG8_MMA(ai, bj, At, Bt) do { __builtin_amdgcn_s_setprio(1); _Pragma("unroll") for (int m = 0; m < 4; ++m) _Pragma("unroll") for (int n = 0; n < 2; ++n) _Pragma("unroll") for (int k = 0; k < 2; ++k) \
;         acc[ai][bj][m][n] = __builtin_amdgcn_mfma_f32_16x16x32_bf16(Bt[n][k], At[m][k], acc[ai][bj][m][n], 0, 0, 0); __builtin_amdgcn_s_setprio(0); } while (0)
; #define PG8_WAIT_V(n) asm volatile("s_waitcnt vmcnt(" #n ")" ::: "memory")
; #define PG8_WAIT_L(n) asm volatile("s_waitcnt lgkmcnt(" #n ")" ::: "memory")
; #define PG8_BAR __builtin_amdgcn_s_barrier()
; #define PG8_SCHED __builtin_amdgcn_sched_barrier(0)
; template <class Epi, class Sched, bool ALIGN_EPI = false, bool SP2 = false>
; __device__ __forceinline__ void gemm_phase(PG8_LAS unsigned char* lds, const Gemm g, const Sched& S, const Epi& E) {
;     ...
;             PG8_LDB(B0, 0, 0); PG8_LDB(B1, 0, 1); PG8_SCHED; PG8_LDA(At, 0, 0); PG8_STAGE(PG8_SA(1, 1), a1 + hstep, voffA);
;             PG8_WAIT_V(8); PG8_WAIT_L(0); PG8_BAR; PG8_MMA(0, 0, At, B0); PG8_MMA(0, 1, At, B1); PG8_BAR; PG8_SCHED;
;             PG8_LDA(At, 0, 1); PG8_STAGE(PG8_SB(0, 0), b2, voffB); PG8_STAGE(PG8_SB(0, 1), b2 + hstep, voffB); PG8_STAGE(PG8_SA(0, 0), a2, voffA);
;             PG8_WAIT_V(8); PG8_WAIT_L(0); PG8_BAR; PG8_MMA(1, 0, At, B0); PG8_MMA(1, 1, At, B1); PG8_BAR; PG8_SCHED;
.LBB0_203:
	ds_read_b128 v[150:153], v161
	ds_read_b128 v[154:157], v161 offset:1024
	ds_read_b128 v[166:169], v161 offset:2048
	ds_read_b128 v[170:173], v161 offset:3072
	ds_read_b128 v[174:177], v162
	ds_read_b128 v[178:181], v162 offset:1024
	ds_read_b128 v[182:185], v162 offset:2048
	ds_read_b128 v[186:189], v162 offset:3072
	s_add_u32 s30, s28, 0xfff80080
	s_addc_u32 s31, s29, -1
	s_cmp_eq_u32 s83, 28
	s_cselect_b32 s35, s6, s31
	s_cselect_b32 s34, s23, s30
	s_cselect_b32 s31, s21, s82
	s_cselect_b32 s30, s70, s71
	s_add_i32 m0, s39, 0xc000
	ds_read_b128 v[190:193], v163
	ds_read_b128 v[194:197], v163 offset:1024
	ds_read_b128 v[198:201], v163 offset:2048
	ds_read_b128 v[206:209], v163 offset:3072
	ds_read_b128 v[210:213], v163 offset:4096
	ds_read_b128 v[214:217], v163 offset:5120
	ds_read_b128 v[218:221], v163 offset:6144
	ds_read_b128 v[222:225], v163 offset:7168
	global_load_lds_dwordx4 v142, s[28:29]
	s_add_i32 m0, s39, 0xe000
	s_nop 0
	global_load_lds_dwordx4 v144, s[28:29]
	s_cmp_eq_u32 s83, -2
	s_cbranch_scc1 .Lgw_a_0_3097
	s_waitcnt vmcnt(8)
	s_branch .Lgw_b_0_3097
.Lgw_a_0_3097:
	s_waitcnt vmcnt(24)
.Lgw_b_0_3097:
	s_waitcnt lgkmcnt(0)
	s_barrier
	s_setprio 1
	s_waitcnt lgkmcnt(0)
	v_mfma_f32_16x16x32_bf16 v[126:129], v[150:153], v[190:193], v[126:129]
	v_mfma_f32_16x16x32_bf16 v[122:125], v[166:169], v[190:193], v[122:125]
	v_mfma_f32_16x16x32_bf16 v[110:113], v[150:153], v[198:201], v[110:113]
	v_mfma_f32_16x16x32_bf16 v[106:109], v[166:169], v[198:201], v[106:109]
	v_mfma_f32_16x16x32_bf16 v[94:97], v[150:153], v[210:213], v[94:97]
	v_mfma_f32_16x16x32_bf16 v[90:93], v[166:169], v[210:213], v[90:93]
	v_mfma_f32_16x16x32_bf16 v[78:81], v[150:153], v[218:221], v[78:81]
	v_mfma_f32_16x16x32_bf16 v[74:77], v[166:169], v[218:221], v[74:77]
	v_mfma_f32_16x16x32_bf16 v[126:129], v[154:157], v[194:197], v[126:129]
	v_mfma_f32_16x16x32_bf16 v[122:125], v[170:173], v[194:197], v[122:125]
	v_mfma_f32_16x16x32_bf16 v[110:113], v[154:157], v[206:209], v[110:113]
	v_mfma_f32_16x16x32_bf16 v[106:109], v[170:173], v[206:209], v[106:109]
	v_mfma_f32_16x16x32_bf16 v[94:97], v[154:157], v[214:217], v[94:97]
	v_mfma_f32_16x16x32_bf16 v[90:93], v[170:173], v[214:217], v[90:93]
	v_mfma_f32_16x16x32_bf16 v[78:81], v[154:157], v[222:225], v[78:81]
	v_mfma_f32_16x16x32_bf16 v[74:77], v[170:173], v[222:225], v[74:77]
	s_setprio 0
	s_setprio 1
	v_mfma_f32_16x16x32_bf16 v[118:121], v[174:177], v[190:193], v[118:121]
	v_mfma_f32_16x16x32_bf16 v[114:117], v[182:185], v[190:193], v[114:117]
	v_mfma_f32_16x16x32_bf16 v[102:105], v[174:177], v[198:201], v[102:105]
	v_mfma_f32_16x16x32_bf16 v[98:101], v[182:185], v[198:201], v[98:101]
	v_mfma_f32_16x16x32_bf16 v[86:89], v[174:177], v[210:213], v[86:89]
	v_mfma_f32_16x16x32_bf16 v[82:85], v[182:185], v[210:213], v[82:85]
	v_mfma_f32_16x16x32_bf16 v[70:73], v[174:177], v[218:221], v[70:73]
	v_mfma_f32_16x16x32_bf16 v[66:69], v[182:185], v[218:221], v[66:69]
	v_mfma_f32_16x16x32_bf16 v[118:121], v[178:181], v[194:197], v[118:121]
	v_mfma_f32_16x16x32_bf16 v[114:117], v[186:189], v[194:197], v[114:117]
	v_mfma_f32_16x16x32_bf16 v[102:105], v[178:181], v[206:209], v[102:105]
	v_mfma_f32_16x16x32_bf16 v[98:101], v[186:189], v[206:209], v[98:101]
	v_mfma_f32_16x16x32_bf16 v[86:89], v[178:181], v[214:217], v[86:89]
	v_mfma_f32_16x16x32_bf16 v[82:85], v[186:189], v[214:217], v[82:85]
	v_mfma_f32_16x16x32_bf16 v[70:73], v[178:181], v[222:225], v[70:73]
	v_mfma_f32_16x16x32_bf16 v[66:69], v[186:189], v[222:225], v[66:69]
	s_setprio 0
	s_barrier
	s_add_i32 s84, s79, s36
	s_add_u32 s64, s30, 0x80
	s_addc_u32 s65, s31, 0
	s_mov_b32 m0, s84
	ds_read_b128 v[190:193], v163 offset:16384
	ds_read_b128 v[194:197], v163 offset:17408
	ds_read_b128 v[198:201], v163 offset:18432
	ds_read_b128 v[206:209], v163 offset:19456
	ds_read_b128 v[210:213], v163 offset:20480
	ds_read_b128 v[214:217], v163 offset:21504
	ds_read_b128 v[218:221], v163 offset:22528
	ds_read_b128 v[222:225], v163 offset:23552
	global_load_lds_dwordx4 v134, s[30:31]
	s_add_i32 m0, s84, 0x2000
	s_add_u32 s84, s30, 0x80000
	s_addc_u32 s85, s31, 0
	s_add_i32 s86, s80, s36
	global_load_lds_dwordx4 v138, s[30:31]
	s_mov_b32 m0, s86
	s_add_u32 s66, s34, 0x80
	s_addc_u32 s67, s35, 0
	global_load_lds_dwordx4 v134, s[84:85]
	s_add_i32 m0, s86, 0x2000
	s_nop 0
	global_load_lds_dwordx4 v138, s[84:85]
	s_mov_b32 m0, s39
	s_nop 0
	global_load_lds_dwordx4 v132, s[34:35]
	s_mov_b32 m0, s40
	s_nop 0
	global_load_lds_dwordx4 v136, s[34:35]
	s_cmp_eq_u32 s83, -2
	s_cbranch_scc1 .Lgw_a_0_3174
	s_waitcnt vmcnt(8)
	s_branch .Lgw_b_0_3174

; #define PG8_STAGE(bufoff, gbase, voff) do { _Pragma("unroll") for (int _i = 0; _i < 2; ++_i) \
;         __builtin_amdgcn_global_load_lds((const unsigned*)((const char*)(gbase) + (voff)[_i]), (PG8_LAS unsigned*)(lds + (bufoff) + ldsw + _i * 8192), 16, 0, 0); } while (0)
; #define PG8_LDA(dst, b, h) do { _Pragma("unroll") for (int m = 0; m < 4; ++m) _Pragma("unroll") for (int k = 0; k < 2; ++k) dst[m][k] = *(const PG8_LAS bf16x8*)(lds + PG8_SA(b, h) + aoff + m * 2048 + k * 1024); } while (0)
; #define PG8_LDB(dst, b, h) do { _Pragma("unroll") for (int n = 0; n < 2; ++n) _Pragma("unroll") for (int k = 0; k < 2; ++k) dst[n][k] = *(const PG8_LAS bf16x8*)(lds + PG8_SB(b, h) + boff + n * 2048 + k * 1024); } while (0)
; #define PG8_MMA(ai, bj, At, Bt) do { __builtin_amdgcn_s_setprio(1); _Pragma("unroll") for (int m = 0; m < 4; ++m) _Pragma("unroll") for (int n = 0; n < 2; ++n) _Pragma("unroll") for (int k = 0; k < 2; ++k) \
;         acc[ai][bj][m][n] = __builtin_amdgcn_mfma_f32_16x16x32_bf16(Bt[n][k], At[m][k], acc[ai][bj][m][n], 0, 0, 0); __builtin_amdgcn_s_setprio(0); } while (0)
; #define PG8_WAIT_V(n) asm volatile("s_waitcnt vmcnt(" #n ")" ::: "memory")
; #define PG8_WAIT_L(n) asm volatile("s_waitcnt lgkmcnt(" #n ")" ::: "memory")
; #define PG8_BAR __builtin_amdgcn_s_barrier()
; #define PG8_SCHED __builtin_amdgcn_sched_barrier(0)
; template <class Epi, class Sched, bool ALIGN_EPI = false, bool SP2 = false>
; __device__ __forceinline__ void gemm_phase(PG8_LAS unsigned char* lds, const Gemm g, const Sched& S, const Epi& E) {
;     ...
;             PG8_WAIT_V(8); PG8_WAIT_L(0); PG8_BAR; PG8_MMA(0, 0, At, B0); PG8_MMA(0, 1, At, B1); PG8_BAR; PG8_SCHED;
;             PG8_LDA(At, 0, 1); PG8_STAGE(PG8_SB(0, 0), b2, voffB); PG8_STAGE(PG8_SB(0, 1), b2 + hstep, voffB); PG8_STAGE(PG8_SA(0, 0), a2, voffA);
;             PG8_WAIT_V(8); PG8_WAIT_L(0); PG8_BAR; PG8_MMA(1, 0, At, B0); PG8_MMA(1, 1, At, B1); PG8_BAR; PG8_SCHED;
;             PG8_LDB(B0, 1, 0); PG8_LDB(B1, 1, 1); PG8_SCHED; PG8_LDA(At, 1, 0); PG8_STAGE(PG8_SA(0, 1), a2 + hstep, voffA);
;             PG8_WAIT_V(8); PG8_WAIT_L(0); PG8_BAR; PG8_MMA(0, 0, At, B0); PG8_MMA(0, 1, At, B1); PG8_BAR; PG8_SCHED;
.Lgw_b_0_3174:
	s_waitcnt lgkmcnt(0)
	s_barrier
	s_setprio 1
	s_waitcnt lgkmcnt(0)
	v_mfma_f32_16x16x32_bf16 v[62:65], v[150:153], v[190:193], v[62:65]
	v_mfma_f32_16x16x32_bf16 v[58:61], v[166:169], v[190:193], v[58:61]
	v_mfma_f32_16x16x32_bf16 v[46:49], v[150:153], v[198:201], v[46:49]
	v_mfma_f32_16x16x32_bf16 v[42:45], v[166:169], v[198:201], v[42:45]
	v_mfma_f32_16x16x32_bf16 v[30:33], v[150:153], v[210:213], v[30:33]
	v_mfma_f32_16x16x32_bf16 v[26:29], v[166:169], v[210:213], v[26:29]
	v_mfma_f32_16x16x32_bf16 v[14:17], v[150:153], v[218:221], v[14:17]
	v_mfma_f32_16x16x32_bf16 v[10:13], v[166:169], v[218:221], v[10:13]
	v_mfma_f32_16x16x32_bf16 v[62:65], v[154:157], v[194:197], v[62:65]
	v_mfma_f32_16x16x32_bf16 v[58:61], v[170:173], v[194:197], v[58:61]
	v_mfma_f32_16x16x32_bf16 v[46:49], v[154:157], v[206:209], v[46:49]
	v_mfma_f32_16x16x32_bf16 v[42:45], v[170:173], v[206:209], v[42:45]
	v_mfma_f32_16x16x32_bf16 v[30:33], v[154:157], v[214:217], v[30:33]
	v_mfma_f32_16x16x32_bf16 v[26:29], v[170:173], v[214:217], v[26:29]
	v_mfma_f32_16x16x32_bf16 v[14:17], v[154:157], v[222:225], v[14:17]
	v_mfma_f32_16x16x32_bf16 v[10:13], v[170:173], v[222:225], v[10:13]
	s_setprio 0
	s_setprio 1
	v_mfma_f32_16x16x32_bf16 v[54:57], v[174:177], v[190:193], v[54:57]
	v_mfma_f32_16x16x32_bf16 v[50:53], v[182:185], v[190:193], v[50:53]
	v_mfma_f32_16x16x32_bf16 v[38:41], v[174:177], v[198:201], v[38:41]
	v_mfma_f32_16x16x32_bf16 v[34:37], v[182:185], v[198:201], v[34:37]
	v_mfma_f32_16x16x32_bf16 v[22:25], v[174:177], v[210:213], v[22:25]
	v_mfma_f32_16x16x32_bf16 v[18:21], v[182:185], v[210:213], v[18:21]
	v_mfma_f32_16x16x32_bf16 v[6:9], v[174:177], v[218:221], v[6:9]
	v_mfma_f32_16x16x32_bf16 v[2:5], v[182:185], v[218:221], v[2:5]
	v_mfma_f32_16x16x32_bf16 v[54:57], v[178:181], v[194:197], v[54:57]
	v_mfma_f32_16x16x32_bf16 v[50:53], v[186:189], v[194:197], v[50:53]
	v_mfma_f32_16x16x32_bf16 v[38:41], v[178:181], v[206:209], v[38:41]
	v_mfma_f32_16x16x32_bf16 v[34:37], v[186:189], v[206:209], v[34:37]
	v_mfma_f32_16x16x32_bf16 v[22:25], v[178:181], v[214:217], v[22:25]
	v_mfma_f32_16x16x32_bf16 v[18:21], v[186:189], v[214:217], v[18:21]
	v_mfma_f32_16x16x32_bf16 v[6:9], v[178:181], v[222:225], v[6:9]
	v_mfma_f32_16x16x32_bf16 v[2:5], v[186:189], v[222:225], v[2:5]
	s_setprio 0
	s_barrier
	s_add_i32 s84, 0, 0x18000
	v_add_u32_e32 v140, s84, v159
	s_add_i32 s85, 0, 0x1c000
	ds_read_b128 v[150:153], v140
	ds_read_b128 v[154:157], v140 offset:1024
	ds_read_b128 v[166:169], v140 offset:2048
	ds_read_b128 v[170:173], v140 offset:3072
	v_add_u32_e32 v140, s85, v159
	ds_read_b128 v[174:177], v140
	ds_read_b128 v[178:181], v140 offset:1024
	ds_read_b128 v[182:185], v140 offset:2048
	ds_read_b128 v[186:189], v140 offset:3072
	s_add_u32 s34, s34, 0x80000
	s_addc_u32 s35, s35, 0
	s_mov_b32 m0, s41
	ds_read_b128 v[190:193], v163 offset:32768
	ds_read_b128 v[194:197], v163 offset:33792
	ds_read_b128 v[198:201], v163 offset:34816
	ds_read_b128 v[206:209], v163 offset:35840
	ds_read_b128 v[210:213], v163 offset:36864
	ds_read_b128 v[214:217], v163 offset:37888
	ds_read_b128 v[218:221], v163 offset:38912
	ds_read_b128 v[222:225], v163 offset:39936
	global_load_lds_dwordx4 v132, s[34:35]
	s_mov_b32 m0, s42
	s_nop 0
	global_load_lds_dwordx4 v136, s[34:35]
	s_waitcnt vmcnt(8)
	s_waitcnt lgkmcnt(0)
	s_barrier
	s_setprio 1
	s_waitcnt lgkmcnt(0)
	v_mfma_f32_16x16x32_bf16 v[126:129], v[150:153], v[190:193], v[126:129]
	v_mfma_f32_16x16x32_bf16 v[122:125], v[166:169], v[190:193], v[122:125]
	v_mfma_f32_16x16x32_bf16 v[110:113], v[150:153], v[198:201], v[110:113]
	v_mfma_f32_16x16x32_bf16 v[106:109], v[166:169], v[198:201], v[106:109]
	v_mfma_f32_16x16x32_bf16 v[94:97], v[150:153], v[210:213], v[94:97]
	v_mfma_f32_16x16x32_bf16 v[90:93], v[166:169], v[210:213], v[90:93]
	v_mfma_f32_16x16x32_bf16 v[78:81], v[150:153], v[218:221], v[78:81]
	v_mfma_f32_16x16x32_bf16 v[74:77], v[166:169], v[218:221], v[74:77]
	v_mfma_f32_16x16x32_bf16 v[126:129], v[154:157], v[194:197], v[126:129]
	v_mfma_f32_16x16x32_bf16 v[122:125], v[170:173], v[194:197], v[122:125]
	v_mfma_f32_16x16x32_bf16 v[110:113], v[154:157], v[206:209], v[110:113]
	v_mfma_f32_16x16x32_bf16 v[106:109], v[170:173], v[206:209], v[106:109]
	v_mfma_f32_16x16x32_bf16 v[94:97], v[154:157], v[214:217], v[94:97]
	v_mfma_f32_16x16x32_bf16 v[90:93], v[170:173], v[214:217], v[90:93]
	v_mfma_f32_16x16x32_bf16 v[78:81], v[154:157], v[222:225], v[78:81]
	v_mfma_f32_16x16x32_bf16 v[74:77], v[170:173], v[222:225], v[74:77]
	s_setprio 0
	s_setprio 1
	v_mfma_f32_16x16x32_bf16 v[118:121], v[174:177], v[190:193], v[118:121]
	v_mfma_f32_16x16x32_bf16 v[114:117], v[182:185], v[190:193], v[114:117]
	v_mfma_f32_16x16x32_bf16 v[102:105], v[174:177], v[198:201], v[102:105]
	v_mfma_f32_16x16x32_bf16 v[98:101], v[182:185], v[198:201], v[98:101]
	v_mfma_f32_16x16x32_bf16 v[86:89], v[174:177], v[210:213], v[86:89]
	v_mfma_f32_16x16x32_bf16 v[82:85], v[182:185], v[210:213], v[82:85]
	v_mfma_f32_16x16x32_bf16 v[70:73], v[174:177], v[218:221], v[70:73]
	v_mfma_f32_16x16x32_bf16 v[66:69], v[182:185], v[218:221], v[66:69]
	v_mfma_f32_16x16x32_bf16 v[118:121], v[178:181], v[194:197], v[118:121]
	v_mfma_f32_16x16x32_bf16 v[114:117], v[186:189], v[194:197], v[114:117]
	v_mfma_f32_16x16x32_bf16 v[102:105], v[178:181], v[206:209], v[102:105]
	v_mfma_f32_16x16x32_bf16 v[98:101], v[186:189], v[206:209], v[98:101]
	v_mfma_f32_16x16x32_bf16 v[86:89], v[178:181], v[214:217], v[86:89]
	v_mfma_f32_16x16x32_bf16 v[82:85], v[186:189], v[214:217], v[82:85]
	v_mfma_f32_16x16x32_bf16 v[70:73], v[178:181], v[222:225], v[70:73]
	v_mfma_f32_16x16x32_bf16 v[66:69], v[186:189], v[222:225], v[66:69]
	s_setprio 0
	s_barrier
; #define PG8_STAGE(bufoff, gbase, voff) do { _Pragma("unroll") for (int _i = 0; _i < 2; ++_i) \
;         __builtin_amdgcn_global_load_lds((const unsigned*)((const char*)(gbase) + (voff)[_i]), (PG8_LAS unsigned*)(lds + (bufoff) + ldsw + _i * 8192), 16, 0, 0); } while (0)
; #define PG8_LDA(dst, b, h) do { _Pragma("unroll") for (int m = 0; m < 4; ++m) _Pragma("unroll") for (int k = 0; k < 2; ++k) dst[m][k] = *(const PG8_LAS bf16x8*)(lds + PG8_SA(b, h) + aoff + m * 2048 + k * 1024); } while (0)
; #define PG8_MMA(ai, bj, At, Bt) do { __builtin_amdgcn_s_setprio(1); _Pragma("unroll") for (int m = 0; m < 4; ++m) _Pragma("unroll") for (int n = 0; n < 2; ++n) _Pragma("unroll") for (int k = 0; k < 2; ++k) \
;         acc[ai][bj][m][n] = __builtin_amdgcn_mfma_f32_16x16x32_bf16(Bt[n][k], At[m][k], acc[ai][bj][m][n], 0, 0, 0); __builtin_amdgcn_s_setprio(0); } while (0)
; #define PG8_WAIT_V(n) asm volatile("s_waitcnt vmcnt(" #n ")" ::: "memory")
; #define PG8_WAIT_L(n) asm volatile("s_waitcnt lgkmcnt(" #n ")" ::: "memory")
; #define PG8_BAR __builtin_amdgcn_s_barrier()
; #define PG8_SCHED __builtin_amdgcn_sched_barrier(0)
; template <class Epi, class Sched, bool ALIGN_EPI = false, bool SP2 = false>
; __device__ __forceinline__ void gemm_phase(PG8_LAS unsigned char* lds, const Gemm g, const Sched& S, const Epi& E) {
;     ...
;         for (int t = 0; t < nt; t += 2) {
;     ...
;             PG8_LDA(At, 1, 1); PG8_STAGE(PG8_SB(1, 0), b3, voffB); PG8_STAGE(PG8_SB(1, 1), b3 + hstep, voffB); PG8_STAGE(PG8_SA(1, 0), a3, voffA);
;             PG8_WAIT_V(8); PG8_WAIT_L(0); PG8_BAR; PG8_MMA(1, 0, At, B0); PG8_MMA(1, 1, At, B1); PG8_BAR; PG8_SCHED;
	s_add_i32 s34, s84, s36
	s_mov_b32 m0, s34
	ds_read_b128 v[190:193], v163 offset:49152
	ds_read_b128 v[194:197], v163 offset:50176
	ds_read_b128 v[198:201], v163 offset:51200
	ds_read_b128 v[206:209], v163 offset:52224
	ds_read_b128 v[210:213], v163 offset:53248
	ds_read_b128 v[214:217], v163 offset:54272
	ds_read_b128 v[218:221], v163 offset:55296
	ds_read_b128 v[222:225], v163 offset:56320
	global_load_lds_dwordx4 v134, s[64:65]
	s_add_i32 m0, s34, 0x2000
	s_add_u32 s30, s30, 0x80080
	s_addc_u32 s31, s31, 0
	s_add_i32 s34, s85, s36
	global_load_lds_dwordx4 v138, s[64:65]
	s_mov_b32 m0, s34
	s_nop 0
	global_load_lds_dwordx4 v134, s[30:31]
	s_add_i32 m0, s34, 0x2000
	s_nop 0
	global_load_lds_dwordx4 v138, s[30:31]
	s_mov_b32 m0, s77
	s_nop 0
	global_load_lds_dwordx4 v132, s[66:67]
	s_mov_b32 m0, s78
	s_nop 0
	global_load_lds_dwordx4 v136, s[66:67]
	s_waitcnt vmcnt(8)
	s_waitcnt lgkmcnt(0)
	s_barrier
	s_setprio 1
	s_waitcnt lgkmcnt(0)
	v_mfma_f32_16x16x32_bf16 v[62:65], v[150:153], v[190:193], v[62:65]
	v_mfma_f32_16x16x32_bf16 v[58:61], v[166:169], v[190:193], v[58:61]
	v_mfma_f32_16x16x32_bf16 v[46:49], v[150:153], v[198:201], v[46:49]
	v_mfma_f32_16x16x32_bf16 v[42:45], v[166:169], v[198:201], v[42:45]
	v_mfma_f32_16x16x32_bf16 v[30:33], v[150:153], v[210:213], v[30:33]
	v_mfma_f32_16x16x32_bf16 v[26:29], v[166:169], v[210:213], v[26:29]
	v_mfma_f32_16x16x32_bf16 v[14:17], v[150:153], v[218:221], v[14:17]
	v_mfma_f32_16x16x32_bf16 v[10:13], v[166:169], v[218:221], v[10:13]
	v_mfma_f32_16x16x32_bf16 v[62:65], v[154:157], v[194:197], v[62:65]
	v_mfma_f32_16x16x32_bf16 v[58:61], v[170:173], v[194:197], v[58:61]
	v_mfma_f32_16x16x32_bf16 v[46:49], v[154:157], v[206:209], v[46:49]
	v_mfma_f32_16x16x32_bf16 v[42:45], v[170:173], v[206:209], v[42:45]
	v_mfma_f32_16x16x32_bf16 v[30:33], v[154:157], v[214:217], v[30:33]
	v_mfma_f32_16x16x32_bf16 v[26:29], v[170:173], v[214:217], v[26:29]
	v_mfma_f32_16x16x32_bf16 v[14:17], v[154:157], v[222:225], v[14:17]
	v_mfma_f32_16x16x32_bf16 v[10:13], v[170:173], v[222:225], v[10:13]
	s_setprio 0
	s_setprio 1
	v_mfma_f32_16x16x32_bf16 v[54:57], v[174:177], v[190:193], v[54:57]
	v_mfma_f32_16x16x32_bf16 v[50:53], v[182:185], v[190:193], v[50:53]
	v_mfma_f32_16x16x32_bf16 v[38:41], v[174:177], v[198:201], v[38:41]
	v_mfma_f32_16x16x32_bf16 v[34:37], v[182:185], v[198:201], v[34:37]
	v_mfma_f32_16x16x32_bf16 v[22:25], v[174:177], v[210:213], v[22:25]
	v_mfma_f32_16x16x32_bf16 v[18:21], v[182:185], v[210:213], v[18:21]
	v_mfma_f32_16x16x32_bf16 v[6:9], v[174:177], v[218:221], v[6:9]
	v_mfma_f32_16x16x32_bf16 v[2:5], v[182:185], v[218:221], v[2:5]
	v_mfma_f32_16x16x32_bf16 v[54:57], v[178:181], v[194:197], v[54:57]
	v_mfma_f32_16x16x32_bf16 v[50:53], v[186:189], v[194:197], v[50:53]
	v_mfma_f32_16x16x32_bf16 v[38:41], v[178:181], v[206:209], v[38:41]
	v_mfma_f32_16x16x32_bf16 v[34:37], v[186:189], v[206:209], v[34:37]
	v_mfma_f32_16x16x32_bf16 v[22:25], v[178:181], v[214:217], v[22:25]
	v_mfma_f32_16x16x32_bf16 v[18:21], v[186:189], v[214:217], v[18:21]
	v_mfma_f32_16x16x32_bf16 v[6:9], v[178:181], v[222:225], v[6:9]
	v_mfma_f32_16x16x32_bf16 v[2:5], v[186:189], v[222:225], v[2:5]
	s_setprio 0
	s_barrier
	s_add_i32 s83, s83, 2
	s_add_u32 s28, s28, 0x100
	s_addc_u32 s29, s29, 0
	s_add_u32 s71, s71, 0x100
	s_addc_u32 s82, s82, 0
	s_cmp_gt_u32 s83, 29
	s_cbranch_scc0 .LBB0_203
	s_and_b64 vcc, exec, s[18:19]
	s_cbranch_vccz .LBB0_206
	s_barrier

; #define PG8_STAGE(bufoff, gbase, voff) do { _Pragma("unroll") for (int _i = 0; _i < 2; ++_i) \
;         __builtin_amdgcn_global_load_lds((const unsigned*)((const char*)(gbase) + (voff)[_i]), (PG8_LAS unsigned*)(lds + (bufoff) + ldsw + _i * 8192), 16, 0, 0); } while (0)
; #define PG8_LDA(dst, b, h) do { _Pragma("unroll") for (int m = 0; m < 4; ++m) _Pragma("unroll") for (int k = 0; k < 2; ++k) dst[m][k] = *(const PG8_LAS bf16x8*)(lds + PG8_SA(b, h) + aoff + m * 2048 + k * 1024); } while (0)
; #define PG8_LDB(dst, b, h) do { _Pragma("unroll") for (int n = 0; n < 2; ++n) _Pragma("unroll") for (int k = 0; k < 2; ++k) dst[n][k] = *(const PG8_LAS bf16x8*)(lds + PG8_SB(b, h) + boff + n * 2048 + k * 1024); } while (0)
; #define PG8_MMA(ai, bj, At, Bt) do { __builtin_amdgcn_s_setprio(1); _Pragma("unroll") for (int m = 0; m < 4; ++m) _Pragma("unroll") for (int n = 0; n < 2; ++n) _Pragma("unroll") for (int k = 0; k < 2; ++k) \
;         acc[ai][bj][m][n] = __builtin_amdgcn_mfma_f32_16x16x32_bf16(Bt[n][k], At[m][k], acc[ai][bj][m][n], 0, 0, 0); __builtin_amdgcn_s_setprio(0); } while (0)
; #define PG8_WAIT_V(n) asm volatile("s_waitcnt vmcnt(" #n ")" ::: "memory")
; #define PG8_WAIT_L(n) asm volatile("s_waitcnt lgkmcnt(" #n ")" ::: "memory")
; #define PG8_BAR __builtin_amdgcn_s_barrier()
; #define PG8_SCHED __builtin_amdgcn_sched_barrier(0)
; template <class Epi, class Sched, bool ALIGN_EPI = false, bool SP2 = false>
; __device__ __forceinline__ void gemm_phase(PG8_LAS unsigned char* lds, const Gemm g, const Sched& S, const Epi& E) {
;     ...
;             PG8_LDB(B0, 0, 0); PG8_LDB(B1, 0, 1); PG8_SCHED; PG8_LDA(At, 0, 0); PG8_STAGE(PG8_SA(1, 1), a1 + hstep, voffA);
;             PG8_WAIT_V(8); PG8_WAIT_L(0); PG8_BAR; PG8_MMA(0, 0, At, B0); PG8_MMA(0, 1, At, B1); PG8_BAR; PG8_SCHED;
;             PG8_LDA(At, 0, 1); PG8_STAGE(PG8_SB(0, 0), b2, voffB); PG8_STAGE(PG8_SB(0, 1), b2 + hstep, voffB); PG8_STAGE(PG8_SA(0, 0), a2, voffA);
;             PG8_WAIT_V(8); PG8_WAIT_L(0); PG8_BAR; PG8_MMA(1, 0, At, B0); PG8_MMA(1, 1, At, B1); PG8_BAR; PG8_SCHED;
.LBB0_765:
	ds_read_b128 v[152:155], v164
	ds_read_b128 v[156:159], v164 offset:1024
	ds_read_b128 v[170:173], v164 offset:2048
	ds_read_b128 v[174:177], v164 offset:3072
	ds_read_b128 v[178:181], v165
	ds_read_b128 v[182:185], v165 offset:1024
	ds_read_b128 v[186:189], v165 offset:2048
	ds_read_b128 v[190:193], v165 offset:3072
	s_add_u32 s30, s28, 0xfff80080
	s_addc_u32 s31, s29, -1
	s_cmp_eq_u32 s85, 28
	s_cselect_b32 s35, s6, s31
	s_cselect_b32 s34, s23, s30
	s_cselect_b32 s31, s21, s84
	s_cselect_b32 s30, s70, s71
	s_add_i32 m0, s41, 0xc000
	ds_read_b128 v[194:197], v166
	ds_read_b128 v[204:207], v166 offset:1024
	ds_read_b128 v[208:211], v166 offset:2048
	ds_read_b128 v[212:215], v166 offset:3072
	ds_read_b128 v[216:219], v166 offset:4096
	ds_read_b128 v[220:223], v166 offset:5120
	ds_read_b128 v[224:227], v166 offset:6144
	ds_read_b128 v[228:231], v166 offset:7168
	global_load_lds_dwordx4 v142, s[28:29]
	s_add_i32 m0, s41, 0xe000
	s_nop 0
	global_load_lds_dwordx4 v144, s[28:29]
	s_cmp_eq_u32 s85, -2
	s_cbranch_scc1 .Lgw_a_1_16604
	s_waitcnt vmcnt(8)
	s_branch .Lgw_b_1_16604

; #define PG8_STAGE(bufoff, gbase, voff) do { _Pragma("unroll") for (int _i = 0; _i < 2; ++_i) \
;         __builtin_amdgcn_global_load_lds((const unsigned*)((const char*)(gbase) + (voff)[_i]), (PG8_LAS unsigned*)(lds + (bufoff) + ldsw + _i * 8192), 16, 0, 0); } while (0)
; #define PG8_LDA(dst, b, h) do { _Pragma("unroll") for (int m = 0; m < 4; ++m) _Pragma("unroll") for (int k = 0; k < 2; ++k) dst[m][k] = *(const PG8_LAS bf16x8*)(lds + PG8_SA(b, h) + aoff + m * 2048 + k * 1024); } while (0)
; #define PG8_MMA(ai, bj, At, Bt) do { __builtin_amdgcn_s_setprio(1); _Pragma("unroll") for (int m = 0; m < 4; ++m) _Pragma("unroll") for (int n = 0; n < 2; ++n) _Pragma("unroll") for (int k = 0; k < 2; ++k) \
;         acc[ai][bj][m][n] = __builtin_amdgcn_mfma_f32_16x16x32_bf16(Bt[n][k], At[m][k], acc[ai][bj][m][n], 0, 0, 0); __builtin_amdgcn_s_setprio(0); } while (0)
; #define PG8_WAIT_V(n) asm volatile("s_waitcnt vmcnt(" #n ")" ::: "memory")
; #define PG8_WAIT_L(n) asm volatile("s_waitcnt lgkmcnt(" #n ")" ::: "memory")
; #define PG8_BAR __builtin_amdgcn_s_barrier()
; #define PG8_SCHED __builtin_amdgcn_sched_barrier(0)
; template <class Epi, class Sched, bool ALIGN_EPI = false, bool SP2 = false>
; __device__ __forceinline__ void gemm_phase(PG8_LAS unsigned char* lds, const Gemm g, const Sched& S, const Epi& E) {
;     ...
;             PG8_WAIT_V(8); PG8_WAIT_L(0); PG8_BAR; PG8_MMA(0, 0, At, B0); PG8_MMA(0, 1, At, B1); PG8_BAR; PG8_SCHED;
;             PG8_LDA(At, 0, 1); PG8_STAGE(PG8_SB(0, 0), b2, voffB); PG8_STAGE(PG8_SB(0, 1), b2 + hstep, voffB); PG8_STAGE(PG8_SA(0, 0), a2, voffA);
;             PG8_WAIT_V(8); PG8_WAIT_L(0); PG8_BAR; PG8_MMA(1, 0, At, B0); PG8_MMA(1, 1, At, B1); PG8_BAR; PG8_SCHED;
.Lgw_b_1_16604:
	s_waitcnt lgkmcnt(0)
	s_barrier
	s_setprio 1
	s_waitcnt lgkmcnt(0)
	v_mfma_f32_16x16x32_bf16 v[126:129], v[152:155], v[194:197], v[126:129]
	v_mfma_f32_16x16x32_bf16 v[122:125], v[170:173], v[194:197], v[122:125]
	v_mfma_f32_16x16x32_bf16 v[110:113], v[152:155], v[208:211], v[110:113]
	v_mfma_f32_16x16x32_bf16 v[106:109], v[170:173], v[208:211], v[106:109]
	v_mfma_f32_16x16x32_bf16 v[94:97], v[152:155], v[216:219], v[94:97]
	v_mfma_f32_16x16x32_bf16 v[90:93], v[170:173], v[216:219], v[90:93]
	v_mfma_f32_16x16x32_bf16 v[78:81], v[152:155], v[224:227], v[78:81]
	v_mfma_f32_16x16x32_bf16 v[74:77], v[170:173], v[224:227], v[74:77]
	v_mfma_f32_16x16x32_bf16 v[126:129], v[156:159], v[204:207], v[126:129]
	v_mfma_f32_16x16x32_bf16 v[122:125], v[174:177], v[204:207], v[122:125]
	v_mfma_f32_16x16x32_bf16 v[110:113], v[156:159], v[212:215], v[110:113]
	v_mfma_f32_16x16x32_bf16 v[106:109], v[174:177], v[212:215], v[106:109]
	v_mfma_f32_16x16x32_bf16 v[94:97], v[156:159], v[220:223], v[94:97]
	v_mfma_f32_16x16x32_bf16 v[90:93], v[174:177], v[220:223], v[90:93]
	v_mfma_f32_16x16x32_bf16 v[78:81], v[156:159], v[228:231], v[78:81]
	v_mfma_f32_16x16x32_bf16 v[74:77], v[174:177], v[228:231], v[74:77]
	s_setprio 0
	s_setprio 1
	v_mfma_f32_16x16x32_bf16 v[118:121], v[178:181], v[194:197], v[118:121]
	v_mfma_f32_16x16x32_bf16 v[114:117], v[186:189], v[194:197], v[114:117]
	v_mfma_f32_16x16x32_bf16 v[102:105], v[178:181], v[208:211], v[102:105]
	v_mfma_f32_16x16x32_bf16 v[98:101], v[186:189], v[208:211], v[98:101]
	v_mfma_f32_16x16x32_bf16 v[86:89], v[178:181], v[216:219], v[86:89]
	v_mfma_f32_16x16x32_bf16 v[82:85], v[186:189], v[216:219], v[82:85]
	v_mfma_f32_16x16x32_bf16 v[70:73], v[178:181], v[224:227], v[70:73]
	v_mfma_f32_16x16x32_bf16 v[66:69], v[186:189], v[224:227], v[66:69]
	v_mfma_f32_16x16x32_bf16 v[118:121], v[182:185], v[204:207], v[118:121]
	v_mfma_f32_16x16x32_bf16 v[114:117], v[190:193], v[204:207], v[114:117]
	v_mfma_f32_16x16x32_bf16 v[102:105], v[182:185], v[212:215], v[102:105]
	v_mfma_f32_16x16x32_bf16 v[98:101], v[190:193], v[212:215], v[98:101]
	v_mfma_f32_16x16x32_bf16 v[86:89], v[182:185], v[220:223], v[86:89]
	v_mfma_f32_16x16x32_bf16 v[82:85], v[190:193], v[220:223], v[82:85]
	v_mfma_f32_16x16x32_bf16 v[70:73], v[182:185], v[228:231], v[70:73]
	v_mfma_f32_16x16x32_bf16 v[66:69], v[190:193], v[228:231], v[66:69]
	s_setprio 0
	s_barrier
	s_add_i32 s64, s81, s36
	s_add_u32 s66, s30, 0x80
	s_addc_u32 s67, s31, 0
	s_mov_b32 m0, s64
	ds_read_b128 v[194:197], v166 offset:16384
	ds_read_b128 v[204:207], v166 offset:17408
	ds_read_b128 v[208:211], v166 offset:18432
	ds_read_b128 v[212:215], v166 offset:19456
	ds_read_b128 v[216:219], v166 offset:20480
	ds_read_b128 v[220:223], v166 offset:21504
	ds_read_b128 v[224:227], v166 offset:22528
	ds_read_b128 v[228:231], v166 offset:23552
	global_load_lds_dwordx4 v134, s[30:31]
	s_add_i32 m0, s64, 0x2000
	s_add_u32 s86, s30, 0x80000
	s_addc_u32 s87, s31, 0
	s_add_i32 s64, s82, s36
	global_load_lds_dwordx4 v138, s[30:31]
	s_mov_b32 m0, s64
	s_add_u32 s68, s34, 0x80
	s_addc_u32 s69, s35, 0
	global_load_lds_dwordx4 v134, s[86:87]
	s_add_i32 m0, s64, 0x2000
	s_nop 0
	global_load_lds_dwordx4 v138, s[86:87]
	s_mov_b32 m0, s41
	s_nop 0
	global_load_lds_dwordx4 v132, s[34:35]
	s_mov_b32 m0, s42
	s_nop 0
	global_load_lds_dwordx4 v136, s[34:35]
	s_cmp_eq_u32 s85, -2
	s_cbranch_scc1 .Lgw_a_1_16681
	s_waitcnt vmcnt(8)
	s_branch .Lgw_b_1_16681

; #define PG8_STAGE(bufoff, gbase, voff) do { _Pragma("unroll") for (int _i = 0; _i < 2; ++_i) \
;         __builtin_amdgcn_global_load_lds((const unsigned*)((const char*)(gbase) + (voff)[_i]), (PG8_LAS unsigned*)(lds + (bufoff) + ldsw + _i * 8192), 16, 0, 0); } while (0)
; #define PG8_LDA(dst, b, h) do { _Pragma("unroll") for (int m = 0; m < 4; ++m) _Pragma("unroll") for (int k = 0; k < 2; ++k) dst[m][k] = *(const PG8_LAS bf16x8*)(lds + PG8_SA(b, h) + aoff + m * 2048 + k * 1024); } while (0)
; #define PG8_LDB(dst, b, h) do { _Pragma("unroll") for (int n = 0; n < 2; ++n) _Pragma("unroll") for (int k = 0; k < 2; ++k) dst[n][k] = *(const PG8_LAS bf16x8*)(lds + PG8_SB(b, h) + boff + n * 2048 + k * 1024); } while (0)
; #define PG8_MMA(ai, bj, At, Bt) do { __builtin_amdgcn_s_setprio(1); _Pragma("unroll") for (int m = 0; m < 4; ++m) _Pragma("unroll") for (int n = 0; n < 2; ++n) _Pragma("unroll") for (int k = 0; k < 2; ++k) \
;         acc[ai][bj][m][n] = __builtin_amdgcn_mfma_f32_16x16x32_bf16(Bt[n][k], At[m][k], acc[ai][bj][m][n], 0, 0, 0); __builtin_amdgcn_s_setprio(0); } while (0)
; #define PG8_WAIT_V(n) asm volatile("s_waitcnt vmcnt(" #n ")" ::: "memory")
; #define PG8_WAIT_L(n) asm volatile("s_waitcnt lgkmcnt(" #n ")" ::: "memory")
; #define PG8_BAR __builtin_amdgcn_s_barrier()
; #define PG8_SCHED __builtin_amdgcn_sched_barrier(0)
; template <class Epi, class Sched, bool ALIGN_EPI = false, bool SP2 = false>
; __device__ __forceinline__ void gemm_phase(PG8_LAS unsigned char* lds, const Gemm g, const Sched& S, const Epi& E) {
;     ...
;             PG8_WAIT_V(8); PG8_WAIT_L(0); PG8_BAR; PG8_MMA(0, 0, At, B0); PG8_MMA(0, 1, At, B1); PG8_BAR; PG8_SCHED;
;             PG8_LDA(At, 0, 1); PG8_STAGE(PG8_SB(0, 0), b2, voffB); PG8_STAGE(PG8_SB(0, 1), b2 + hstep, voffB); PG8_STAGE(PG8_SA(0, 0), a2, voffA);
;             PG8_WAIT_V(8); PG8_WAIT_L(0); PG8_BAR; PG8_MMA(1, 0, At, B0); PG8_MMA(1, 1, At, B1); PG8_BAR; PG8_SCHED;
;             PG8_LDB(B0, 1, 0); PG8_LDB(B1, 1, 1); PG8_SCHED; PG8_LDA(At, 1, 0); PG8_STAGE(PG8_SA(0, 1), a2 + hstep, voffA);
;             PG8_WAIT_V(8); PG8_WAIT_L(0); PG8_BAR; PG8_MMA(0, 0, At, B0); PG8_MMA(0, 1, At, B1); PG8_BAR; PG8_SCHED;
.Lgw_b_1_16681:
	s_waitcnt lgkmcnt(0)
	s_barrier
	s_setprio 1
	s_waitcnt lgkmcnt(0)
	v_mfma_f32_16x16x32_bf16 v[62:65], v[152:155], v[194:197], v[62:65]
	v_mfma_f32_16x16x32_bf16 v[58:61], v[170:173], v[194:197], v[58:61]
	v_mfma_f32_16x16x32_bf16 v[46:49], v[152:155], v[208:211], v[46:49]
	v_mfma_f32_16x16x32_bf16 v[42:45], v[170:173], v[208:211], v[42:45]
	v_mfma_f32_16x16x32_bf16 v[30:33], v[152:155], v[216:219], v[30:33]
	v_mfma_f32_16x16x32_bf16 v[26:29], v[170:173], v[216:219], v[26:29]
	v_mfma_f32_16x16x32_bf16 v[14:17], v[152:155], v[224:227], v[14:17]
	v_mfma_f32_16x16x32_bf16 v[10:13], v[170:173], v[224:227], v[10:13]
	v_mfma_f32_16x16x32_bf16 v[62:65], v[156:159], v[204:207], v[62:65]
	v_mfma_f32_16x16x32_bf16 v[58:61], v[174:177], v[204:207], v[58:61]
	v_mfma_f32_16x16x32_bf16 v[46:49], v[156:159], v[212:215], v[46:49]
	v_mfma_f32_16x16x32_bf16 v[42:45], v[174:177], v[212:215], v[42:45]
	v_mfma_f32_16x16x32_bf16 v[30:33], v[156:159], v[220:223], v[30:33]
	v_mfma_f32_16x16x32_bf16 v[26:29], v[174:177], v[220:223], v[26:29]
	v_mfma_f32_16x16x32_bf16 v[14:17], v[156:159], v[228:231], v[14:17]
	v_mfma_f32_16x16x32_bf16 v[10:13], v[174:177], v[228:231], v[10:13]
	s_setprio 0
	s_setprio 1
	v_mfma_f32_16x16x32_bf16 v[54:57], v[178:181], v[194:197], v[54:57]
	v_mfma_f32_16x16x32_bf16 v[50:53], v[186:189], v[194:197], v[50:53]
	v_mfma_f32_16x16x32_bf16 v[38:41], v[178:181], v[208:211], v[38:41]
	v_mfma_f32_16x16x32_bf16 v[34:37], v[186:189], v[208:211], v[34:37]
	v_mfma_f32_16x16x32_bf16 v[22:25], v[178:181], v[216:219], v[22:25]
	v_mfma_f32_16x16x32_bf16 v[18:21], v[186:189], v[216:219], v[18:21]
	v_mfma_f32_16x16x32_bf16 v[6:9], v[178:181], v[224:227], v[6:9]
	v_mfma_f32_16x16x32_bf16 v[2:5], v[186:189], v[224:227], v[2:5]
	v_mfma_f32_16x16x32_bf16 v[54:57], v[182:185], v[204:207], v[54:57]
	v_mfma_f32_16x16x32_bf16 v[50:53], v[190:193], v[204:207], v[50:53]
	v_mfma_f32_16x16x32_bf16 v[38:41], v[182:185], v[212:215], v[38:41]
	v_mfma_f32_16x16x32_bf16 v[34:37], v[190:193], v[212:215], v[34:37]
	v_mfma_f32_16x16x32_bf16 v[22:25], v[182:185], v[220:223], v[22:25]
	v_mfma_f32_16x16x32_bf16 v[18:21], v[190:193], v[220:223], v[18:21]
	v_mfma_f32_16x16x32_bf16 v[6:9], v[182:185], v[228:231], v[6:9]
	v_mfma_f32_16x16x32_bf16 v[2:5], v[190:193], v[228:231], v[2:5]
	s_setprio 0
	s_barrier
	s_add_i32 s64, 0, 0x18000
	v_add_u32_e32 v140, s64, v160
	s_add_i32 s65, 0, 0x1c000
	ds_read_b128 v[152:155], v140
	ds_read_b128 v[156:159], v140 offset:1024
	ds_read_b128 v[170:173], v140 offset:2048
	ds_read_b128 v[174:177], v140 offset:3072
	v_add_u32_e32 v140, s65, v160
	ds_read_b128 v[178:181], v140
	ds_read_b128 v[182:185], v140 offset:1024
	ds_read_b128 v[186:189], v140 offset:2048
	ds_read_b128 v[190:193], v140 offset:3072
	s_add_u32 s34, s34, 0x80000
	s_addc_u32 s35, s35, 0
	s_mov_b32 m0, s43
	ds_read_b128 v[194:197], v166 offset:32768
	ds_read_b128 v[204:207], v166 offset:33792
	ds_read_b128 v[208:211], v166 offset:34816
	ds_read_b128 v[212:215], v166 offset:35840
	ds_read_b128 v[216:219], v166 offset:36864
	ds_read_b128 v[220:223], v166 offset:37888
	ds_read_b128 v[224:227], v166 offset:38912
	ds_read_b128 v[228:231], v166 offset:39936
	global_load_lds_dwordx4 v132, s[34:35]
	s_mov_b32 m0, s44
	s_nop 0
	global_load_lds_dwordx4 v136, s[34:35]
	s_waitcnt vmcnt(8)
	s_waitcnt lgkmcnt(0)
	s_barrier
	s_setprio 1
	s_waitcnt lgkmcnt(0)
	v_mfma_f32_16x16x32_bf16 v[126:129], v[152:155], v[194:197], v[126:129]
	v_mfma_f32_16x16x32_bf16 v[122:125], v[170:173], v[194:197], v[122:125]
	v_mfma_f32_16x16x32_bf16 v[110:113], v[152:155], v[208:211], v[110:113]
	v_mfma_f32_16x16x32_bf16 v[106:109], v[170:173], v[208:211], v[106:109]
	v_mfma_f32_16x16x32_bf16 v[94:97], v[152:155], v[216:219], v[94:97]
	v_mfma_f32_16x16x32_bf16 v[90:93], v[170:173], v[216:219], v[90:93]
	v_mfma_f32_16x16x32_bf16 v[78:81], v[152:155], v[224:227], v[78:81]
	v_mfma_f32_16x16x32_bf16 v[74:77], v[170:173], v[224:227], v[74:77]
	v_mfma_f32_16x16x32_bf16 v[126:129], v[156:159], v[204:207], v[126:129]
	v_mfma_f32_16x16x32_bf16 v[122:125], v[174:177], v[204:207], v[122:125]
	v_mfma_f32_16x16x32_bf16 v[110:113], v[156:159], v[212:215], v[110:113]
	v_mfma_f32_16x16x32_bf16 v[106:109], v[174:177], v[212:215], v[106:109]
	v_mfma_f32_16x16x32_bf16 v[94:97], v[156:159], v[220:223], v[94:97]
	v_mfma_f32_16x16x32_bf16 v[90:93], v[174:177], v[220:223], v[90:93]
	v_mfma_f32_16x16x32_bf16 v[78:81], v[156:159], v[228:231], v[78:81]
	v_mfma_f32_16x16x32_bf16 v[74:77], v[174:177], v[228:231], v[74:77]
	s_setprio 0
	s_setprio 1
	v_mfma_f32_16x16x32_bf16 v[118:121], v[178:181], v[194:197], v[118:121]
	v_mfma_f32_16x16x32_bf16 v[114:117], v[186:189], v[194:197], v[114:117]
	v_mfma_f32_16x16x32_bf16 v[102:105], v[178:181], v[208:211], v[102:105]
	v_mfma_f32_16x16x32_bf16 v[98:101], v[186:189], v[208:211], v[98:101]
	v_mfma_f32_16x16x32_bf16 v[86:89], v[178:181], v[216:219], v[86:89]
	v_mfma_f32_16x16x32_bf16 v[82:85], v[186:189], v[216:219], v[82:85]
	v_mfma_f32_16x16x32_bf16 v[70:73], v[178:181], v[224:227], v[70:73]
	v_mfma_f32_16x16x32_bf16 v[66:69], v[186:189], v[224:227], v[66:69]
	v_mfma_f32_16x16x32_bf16 v[118:121], v[182:185], v[204:207], v[118:121]
	v_mfma_f32_16x16x32_bf16 v[114:117], v[190:193], v[204:207], v[114:117]
	v_mfma_f32_16x16x32_bf16 v[102:105], v[182:185], v[212:215], v[102:105]
	v_mfma_f32_16x16x32_bf16 v[98:101], v[190:193], v[212:215], v[98:101]
	v_mfma_f32_16x16x32_bf16 v[86:89], v[182:185], v[220:223], v[86:89]
	v_mfma_f32_16x16x32_bf16 v[82:85], v[190:193], v[220:223], v[82:85]
	v_mfma_f32_16x16x32_bf16 v[70:73], v[182:185], v[228:231], v[70:73]
	v_mfma_f32_16x16x32_bf16 v[66:69], v[190:193], v[228:231], v[66:69]
	s_setprio 0
	s_barrier
; #define PG8_STAGE(bufoff, gbase, voff) do { _Pragma("unroll") for (int _i = 0; _i < 2; ++_i) \
;         __builtin_amdgcn_global_load_lds((const unsigned*)((const char*)(gbase) + (voff)[_i]), (PG8_LAS unsigned*)(lds + (bufoff) + ldsw + _i * 8192), 16, 0, 0); } while (0)
; #define PG8_LDA(dst, b, h) do { _Pragma("unroll") for (int m = 0; m < 4; ++m) _Pragma("unroll") for (int k = 0; k < 2; ++k) dst[m][k] = *(const PG8_LAS bf16x8*)(lds + PG8_SA(b, h) + aoff + m * 2048 + k * 1024); } while (0)
; #define PG8_MMA(ai, bj, At, Bt) do { __builtin_amdgcn_s_setprio(1); _Pragma("unroll") for (int m = 0; m < 4; ++m) _Pragma("unroll") for (int n = 0; n < 2; ++n) _Pragma("unroll") for (int k = 0; k < 2; ++k) \
;         acc[ai][bj][m][n] = __builtin_amdgcn_mfma_f32_16x16x32_bf16(Bt[n][k], At[m][k], acc[ai][bj][m][n], 0, 0, 0); __builtin_amdgcn_s_setprio(0); } while (0)
; #define PG8_WAIT_V(n) asm volatile("s_waitcnt vmcnt(" #n ")" ::: "memory")
; #define PG8_WAIT_L(n) asm volatile("s_waitcnt lgkmcnt(" #n ")" ::: "memory")
; #define PG8_BAR __builtin_amdgcn_s_barrier()
; #define PG8_SCHED __builtin_amdgcn_sched_barrier(0)
; template <class Epi, class Sched, bool ALIGN_EPI = false, bool SP2 = false>
; __device__ __forceinline__ void gemm_phase(PG8_LAS unsigned char* lds, const Gemm g, const Sched& S, const Epi& E) {
;     ...
;         for (int t = 0; t < nt; t += 2) {
;     ...
;             PG8_LDA(At, 1, 1); PG8_STAGE(PG8_SB(1, 0), b3, voffB); PG8_STAGE(PG8_SB(1, 1), b3 + hstep, voffB); PG8_STAGE(PG8_SA(1, 0), a3, voffA);
;             PG8_WAIT_V(8); PG8_WAIT_L(0); PG8_BAR; PG8_MMA(1, 0, At, B0); PG8_MMA(1, 1, At, B1); PG8_BAR; PG8_SCHED;
	s_add_i32 s34, s64, s36
	s_mov_b32 m0, s34
	ds_read_b128 v[194:197], v166 offset:49152
	ds_read_b128 v[204:207], v166 offset:50176
	ds_read_b128 v[208:211], v166 offset:51200
	ds_read_b128 v[212:215], v166 offset:52224
	ds_read_b128 v[216:219], v166 offset:53248
	ds_read_b128 v[220:223], v166 offset:54272
	ds_read_b128 v[224:227], v166 offset:55296
	ds_read_b128 v[228:231], v166 offset:56320
	global_load_lds_dwordx4 v134, s[66:67]
	s_add_i32 m0, s34, 0x2000
	s_add_u32 s30, s30, 0x80080
	s_addc_u32 s31, s31, 0
	s_add_i32 s34, s65, s36
	global_load_lds_dwordx4 v138, s[66:67]
	s_mov_b32 m0, s34
	s_nop 0
	global_load_lds_dwordx4 v134, s[30:31]
	s_add_i32 m0, s34, 0x2000
	s_nop 0
	global_load_lds_dwordx4 v138, s[30:31]
	s_mov_b32 m0, s79
	s_nop 0
	global_load_lds_dwordx4 v132, s[68:69]
	s_mov_b32 m0, s80
	s_nop 0
	global_load_lds_dwordx4 v136, s[68:69]
	s_waitcnt vmcnt(8)
	s_waitcnt lgkmcnt(0)
	s_barrier
	s_setprio 1
	s_waitcnt lgkmcnt(0)
	v_mfma_f32_16x16x32_bf16 v[62:65], v[152:155], v[194:197], v[62:65]
	v_mfma_f32_16x16x32_bf16 v[58:61], v[170:173], v[194:197], v[58:61]
	v_mfma_f32_16x16x32_bf16 v[46:49], v[152:155], v[208:211], v[46:49]
	v_mfma_f32_16x16x32_bf16 v[42:45], v[170:173], v[208:211], v[42:45]
	v_mfma_f32_16x16x32_bf16 v[30:33], v[152:155], v[216:219], v[30:33]
	v_mfma_f32_16x16x32_bf16 v[26:29], v[170:173], v[216:219], v[26:29]
	v_mfma_f32_16x16x32_bf16 v[14:17], v[152:155], v[224:227], v[14:17]
	v_mfma_f32_16x16x32_bf16 v[10:13], v[170:173], v[224:227], v[10:13]
	v_mfma_f32_16x16x32_bf16 v[62:65], v[156:159], v[204:207], v[62:65]
	v_mfma_f32_16x16x32_bf16 v[58:61], v[174:177], v[204:207], v[58:61]
	v_mfma_f32_16x16x32_bf16 v[46:49], v[156:159], v[212:215], v[46:49]
	v_mfma_f32_16x16x32_bf16 v[42:45], v[174:177], v[212:215], v[42:45]
	v_mfma_f32_16x16x32_bf16 v[30:33], v[156:159], v[220:223], v[30:33]
	v_mfma_f32_16x16x32_bf16 v[26:29], v[174:177], v[220:223], v[26:29]
	v_mfma_f32_16x16x32_bf16 v[14:17], v[156:159], v[228:231], v[14:17]
	v_mfma_f32_16x16x32_bf16 v[10:13], v[174:177], v[228:231], v[10:13]
	s_setprio 0
	s_setprio 1
	v_mfma_f32_16x16x32_bf16 v[54:57], v[178:181], v[194:197], v[54:57]
	v_mfma_f32_16x16x32_bf16 v[50:53], v[186:189], v[194:197], v[50:53]
	v_mfma_f32_16x16x32_bf16 v[38:41], v[178:181], v[208:211], v[38:41]
	v_mfma_f32_16x16x32_bf16 v[34:37], v[186:189], v[208:211], v[34:37]
	v_mfma_f32_16x16x32_bf16 v[22:25], v[178:181], v[216:219], v[22:25]
	v_mfma_f32_16x16x32_bf16 v[18:21], v[186:189], v[216:219], v[18:21]
	v_mfma_f32_16x16x32_bf16 v[6:9], v[178:181], v[224:227], v[6:9]
	v_mfma_f32_16x16x32_bf16 v[2:5], v[186:189], v[224:227], v[2:5]
	v_mfma_f32_16x16x32_bf16 v[54:57], v[182:185], v[204:207], v[54:57]
	v_mfma_f32_16x16x32_bf16 v[50:53], v[190:193], v[204:207], v[50:53]
	v_mfma_f32_16x16x32_bf16 v[38:41], v[182:185], v[212:215], v[38:41]
	v_mfma_f32_16x16x32_bf16 v[34:37], v[190:193], v[212:215], v[34:37]
	v_mfma_f32_16x16x32_bf16 v[22:25], v[182:185], v[220:223], v[22:25]
	v_mfma_f32_16x16x32_bf16 v[18:21], v[190:193], v[220:223], v[18:21]
	v_mfma_f32_16x16x32_bf16 v[6:9], v[182:185], v[228:231], v[6:9]
	v_mfma_f32_16x16x32_bf16 v[2:5], v[190:193], v[228:231], v[2:5]
	s_setprio 0
	s_barrier
	s_add_i32 s85, s85, 2
	s_add_u32 s28, s28, 0x100
	s_addc_u32 s29, s29, 0
	s_add_u32 s71, s71, 0x100
	s_addc_u32 s84, s84, 0
	s_cmp_gt_u32 s85, 29
	s_cbranch_scc0 .LBB0_765
	s_and_b64 vcc, exec, s[18:19]
	s_cbranch_vccz .LBB0_768
	s_barrier
